# pipelined RES/MERGE/STORE epilogues plus prologue x-to-hi/lo conversion loop with all four row loads issued up front (counted vmcnt)
# baseline (speedup 1.0000x reference)
; __device__ __forceinline__ unsigned cvtpk(float lo, float hi) { f32x2_t v = {lo, hi}; bf16x2_t b = __builtin_convertvector(v, bf16x2_t); return __builtin_bit_cast(unsigned, b); }
; __device__ __forceinline__ float dot4(f32x4 a) { return (a[0] * a[0] + a[1] * a[1]) + (a[2] * a[2] + a[3] * a[3]); }
; __global__ void __launch_bounds__(512) fwd_megakernel(Args a) {
;     ...
;         for (int m = gw; m < MTOK; m += NGW) {
;             const f32x4* xr = (const f32x4*)(x + (size_t)m * DM) + lane;
;             u32x2* hb = (u32x2*)(AO + (size_t)m * DM) + lane; u32x2* lb = (u32x2*)((bf16_t*)(ws + WS_LO) + (size_t)m * DM) + lane;
;             float s2 = 0.f;
; #pragma unroll
;             for (int j = 0; j < 4; ++j) { const f32x4 v = xr[64 * j]; s2 += dot4(v); u32x2 w; w.x = cvtpk(v[0], v[1]); w.y = cvtpk(v[2], v[3]); hb[64 * j] = w;
;                 f32x4 g; g[0] = __uint_as_float(w.x << 16); g[1] = __uint_as_float(w.x & 0xffff0000u); g[2] = __uint_as_float(w.y << 16); g[3] = __uint_as_float(w.y & 0xffff0000u);
;                 u32x2 wl; wl.x = cvtpk(v[0] - g[0], v[1] - g[1]); wl.y = cvtpk(v[2] - g[2], v[3] - g[3]); lb[64 * j] = wl; }
;             s2 = wave_sum(s2);
;             if (lane == 0) SS[m] = s2;
;         }
.LBB0_135:
	global_load_dwordx4 v[60:63], v[6:7], off offset:-2048
	global_load_dwordx4 v[64:67], v[6:7], off offset:-1024
	global_load_dwordx4 v[68:71], v[6:7], off
	global_load_dwordx4 v[72:75], v[6:7], off offset:1024
	v_lshl_add_u64 v[18:19], s[80:81], 0, v[2:3]
	v_add_co_u32_e32 v30, vcc, s5, v18
	s_nop 1
	v_addc_co_u32_e32 v31, vcc, 0, v19, vcc
	v_add_co_u32_e32 v32, vcc, s7, v18
	s_nop 1
	v_addc_co_u32_e32 v33, vcc, 0, v19, vcc
	s_waitcnt vmcnt(3)
	v_cvt_pk_bf16_f32 v76, v60, v61
	v_cvt_pk_bf16_f32 v77, v62, v63
	global_store_dwordx2 v[30:31], v[76:77], off
	v_lshlrev_b32_e32 v78, 16, v76
	v_and_b32_e32 v79, 0xffff0000, v76
	v_lshlrev_b32_e32 v80, 16, v77
	v_and_b32_e32 v81, 0xffff0000, v77
	v_pk_add_f32 v[78:79], v[60:61], v[78:79] neg_lo:[0,1] neg_hi:[0,1]
	v_pk_add_f32 v[80:81], v[62:63], v[80:81] neg_lo:[0,1] neg_hi:[0,1]
	v_cvt_pk_bf16_f32 v82, v78, v79
	v_cvt_pk_bf16_f32 v83, v80, v81
	global_store_dwordx2 v[32:33], v[82:83], off
	v_mul_f32_e32 v4, v61, v61
	v_mul_f32_e32 v13, v63, v63
	v_fmac_f32_e32 v4, v60, v60
	v_fmac_f32_e32 v13, v62, v62
	v_add_f32_e32 v4, v4, v13
	s_waitcnt vmcnt(4)
	v_cvt_pk_bf16_f32 v84, v64, v65
	v_cvt_pk_bf16_f32 v85, v66, v67
	global_store_dwordx2 v[30:31], v[84:85], off offset:512
	v_lshlrev_b32_e32 v86, 16, v84
	v_and_b32_e32 v87, 0xffff0000, v84
	v_lshlrev_b32_e32 v88, 16, v85
	v_and_b32_e32 v89, 0xffff0000, v85
	v_pk_add_f32 v[86:87], v[64:65], v[86:87] neg_lo:[0,1] neg_hi:[0,1]
	v_pk_add_f32 v[88:89], v[66:67], v[88:89] neg_lo:[0,1] neg_hi:[0,1]
	v_cvt_pk_bf16_f32 v90, v86, v87
	v_cvt_pk_bf16_f32 v91, v88, v89
	global_store_dwordx2 v[32:33], v[90:91], off offset:512
	v_mul_f32_e32 v13, v65, v65
	v_mul_f32_e32 v14, v67, v67
	v_fmac_f32_e32 v13, v64, v64
	v_fmac_f32_e32 v14, v66, v66
	v_add_f32_e32 v13, v13, v14
	v_add_f32_e32 v4, v4, v13
	s_waitcnt vmcnt(5)
	v_cvt_pk_bf16_f32 v92, v68, v69
	v_cvt_pk_bf16_f32 v93, v70, v71
	global_store_dwordx2 v[30:31], v[92:93], off offset:1024
	v_lshlrev_b32_e32 v94, 16, v92
	v_and_b32_e32 v95, 0xffff0000, v92
	v_lshlrev_b32_e32 v96, 16, v93
	v_and_b32_e32 v97, 0xffff0000, v93
	v_pk_add_f32 v[94:95], v[68:69], v[94:95] neg_lo:[0,1] neg_hi:[0,1]
	v_pk_add_f32 v[96:97], v[70:71], v[96:97] neg_lo:[0,1] neg_hi:[0,1]
	v_cvt_pk_bf16_f32 v98, v94, v95
	v_cvt_pk_bf16_f32 v99, v96, v97
	global_store_dwordx2 v[32:33], v[98:99], off offset:1024
	v_mul_f32_e32 v13, v69, v69
	v_mul_f32_e32 v14, v71, v71
	v_fmac_f32_e32 v13, v68, v68
	v_fmac_f32_e32 v14, v70, v70
	v_add_f32_e32 v13, v13, v14
	v_add_f32_e32 v4, v4, v13
	s_waitcnt vmcnt(6)
	v_cvt_pk_bf16_f32 v100, v72, v73
	v_cvt_pk_bf16_f32 v101, v74, v75
	global_store_dwordx2 v[30:31], v[100:101], off offset:1536
	v_lshlrev_b32_e32 v102, 16, v100
	v_and_b32_e32 v103, 0xffff0000, v100
	v_lshlrev_b32_e32 v104, 16, v101
	v_and_b32_e32 v105, 0xffff0000, v101
	v_pk_add_f32 v[102:103], v[72:73], v[102:103] neg_lo:[0,1] neg_hi:[0,1]
	v_pk_add_f32 v[104:105], v[74:75], v[104:105] neg_lo:[0,1] neg_hi:[0,1]
	v_cvt_pk_bf16_f32 v106, v102, v103
	v_cvt_pk_bf16_f32 v107, v104, v105
	global_store_dwordx2 v[32:33], v[106:107], off offset:1536
	v_mul_f32_e32 v13, v73, v73
	v_mul_f32_e32 v14, v75, v75
	v_fmac_f32_e32 v13, v72, v72
	v_fmac_f32_e32 v14, v74, v74
	v_add_f32_e32 v13, v13, v14
	v_add_f32_e32 v4, v4, v13
	ds_bpermute_b32 v13, v1, v4
	s_waitcnt lgkmcnt(0)
	v_add_f32_e32 v4, v4, v13
	ds_bpermute_b32 v13, v8, v4
	s_waitcnt lgkmcnt(0)
	v_add_f32_e32 v4, v4, v13
	ds_bpermute_b32 v13, v9, v4
	s_waitcnt lgkmcnt(0)
	v_add_f32_e32 v4, v4, v13
	ds_bpermute_b32 v13, v10, v4
	s_waitcnt lgkmcnt(0)
	v_add_f32_e32 v4, v4, v13
	ds_bpermute_b32 v13, v11, v4
	s_waitcnt lgkmcnt(0)
	v_add_f32_e32 v4, v4, v13
	ds_bpermute_b32 v13, v12, v4
	s_and_saveexec_b64 s[12:13], s[0:1]
	s_cbranch_execz .LBB0_134
	s_mov_b64 s[16:17], s[80:81]
	s_add_u32 s16, s16, s14
	s_addc_u32 s17, s17, s15
	s_waitcnt lgkmcnt(0)
	v_add_f32_e32 v4, v4, v13
	s_mov_b64 s[18:19], s[82:83]
	global_store_dword v5, v4, s[16:17]
	s_branch .LBB0_134
